# hand-written DSA indexer scan loop: pipelined MFMA, branch-free insertion, scalar counters (plus batched scans)
# speedup vs baseline: 1.0214x; 1.0214x over previous
; __device__ __forceinline__ void dsa_wave(const Params& p, int rank, char* sm) {
;     ...
;   Tf[0] = Tf[1] = Tf[2] = Tf[3] = -__builtin_inff();
;   const int ntile = (l0 + 7) / 32 + 1;
;   const bf* kif = p.KIF + (size_t)b * 512 * 2048 + lane * 8;
;   bf16x8 bqA[4][4], bqB[4][4];
; #pragma unroll
;   for (int s = 0; s < 4; s++) {
;     const int ts = s < ntile ? s : ntile - 1;
; #pragma unroll
;     for (int ks = 0; ks < 4; ks++) bqA[s][ks] = *(const bf16x8*)(kif + (size_t)ts * 2048 + ks * 512);
;   }
.LBB0_543:
	v_mov_b32_e32 v144, 0
	v_mov_b32_e32 v173, 0
	s_and_saveexec_b64 s[42:43], s[6:7]
	s_cbranch_execz .LBB0_1451
	v_mov_b32_e32 v216, 0
	v_mov_b32_e32 v218, 0
	v_mov_b32_e32 v220, 0
	v_mov_b32_e32 v222, 0
	v_mov_b32_e32 v217, 0xff800000
	v_mov_b32_e32 v219, 0xff800000
	v_mov_b32_e32 v221, 0xff800000
	v_mov_b32_e32 v223, 0xff800000
	v_mov_b32_e32 v144, 0
	v_mov_b32_e32 v173, 0
	v_lshlrev_b32_e32 v11, 4, v151
	v_readfirstlane_b32 s61, v189
	v_readfirstlane_b32 s62, v203
	v_readlane_b32 s64, v253, 22
	v_readlane_b32 s65, v253, 23
	s_bfe_u32 s62, s62, 0x10006
	s_lshl_b32 s62, s62, 21
	s_add_u32 s64, s64, s62
	s_addc_u32 s65, s65, 0
	s_mov_b32 s52, 0
	s_mov_b32 s53, 0
	s_mov_b32 s54, 0
	s_mov_b32 s55, 0
	s_mov_b32 s56, 0
	s_mov_b32 s57, 0
	s_mov_b32 s58, 0
	s_mov_b32 s59, 0
	s_mov_b32 s60, 0
	s_min_u32 s62, 0, s61
	s_lshl_b32 s62, s62, 12
	v_add_u32_e32 v14, s62, v11
	global_load_dwordx4 v[32:35], v14, s[64:65]
	global_load_dwordx4 v[36:39], v14, s[64:65] offset:1024
	global_load_dwordx4 v[40:43], v14, s[64:65] offset:2048
	global_load_dwordx4 v[44:47], v14, s[64:65] offset:3072
	s_min_u32 s62, 1, s61
	s_lshl_b32 s62, s62, 12
	v_add_u32_e32 v14, s62, v11
	global_load_dwordx4 v[48:51], v14, s[64:65]
	global_load_dwordx4 v[52:55], v14, s[64:65] offset:1024
	global_load_dwordx4 v[56:59], v14, s[64:65] offset:2048
	global_load_dwordx4 v[60:63], v14, s[64:65] offset:3072
	s_min_u32 s62, 2, s61
	s_lshl_b32 s62, s62, 12
	v_add_u32_e32 v14, s62, v11
	global_load_dwordx4 v[64:67], v14, s[64:65]
	global_load_dwordx4 v[68:71], v14, s[64:65] offset:1024
	global_load_dwordx4 v[72:75], v14, s[64:65] offset:2048
	global_load_dwordx4 v[76:79], v14, s[64:65] offset:3072
	s_waitcnt vmcnt(8)
	v_mfma_f32_32x32x16_bf16 v[96:111], v[24:27], v[32:35], 0
	v_mfma_f32_32x32x16_bf16 v[96:111], v[16:19], v[36:39], v[96:111]
	v_mfma_f32_32x32x16_bf16 v[96:111], v[20:23], v[40:43], v[96:111]
	v_mfma_f32_32x32x16_bf16 v[96:111], v[28:31], v[44:47], v[96:111]
.Lidx_loop:
.Lidx_tile0:
	s_add_u32 s62, s60, 3
	s_min_u32 s62, s62, s61
	s_lshl_b32 s62, s62, 12
	v_add_u32_e32 v14, s62, v11
	global_load_dwordx4 v[80:83], v14, s[64:65]
	global_load_dwordx4 v[84:87], v14, s[64:65] offset:1024
	global_load_dwordx4 v[88:91], v14, s[64:65] offset:2048
	global_load_dwordx4 v[92:95], v14, s[64:65] offset:3072
	s_max_u32 s62, s52, s53
	s_max_u32 s63, s54, s55
	s_max_u32 s62, s62, s63
	s_max_u32 s63, s56, s57
	s_max_u32 s62, s62, s63
	s_max_u32 s63, s58, s59
	s_max_u32 s62, s62, s63
	s_cmp_gt_u32 s62, s80
	s_cbranch_scc1 .Lidx_compact0
.Lidx_resume0:
	s_waitcnt vmcnt(8)
	v_mfma_f32_32x32x16_bf16 v[112:127], v[24:27], v[48:51], 0
	v_mfma_f32_32x32x16_bf16 v[112:127], v[16:19], v[52:55], v[112:127]
	v_mfma_f32_32x32x16_bf16 v[112:127], v[20:23], v[56:59], v[112:127]
	v_mfma_f32_32x32x16_bf16 v[112:127], v[28:31], v[60:63], v[112:127]
	s_lshl_b32 s62, s60, 5
	v_add_u32_e32 v215, s62, v157
	v_sub_u32_e32 v13, 0x3fff, v215
	v_max_i32_e32 v0, 0, v96
	v_max_i32_e32 v1, 0, v97
	v_mul_f32_e32 v4, v159, v0
	v_max_i32_e32 v2, 0, v98
	v_fmac_f32_e32 v4, v1, v174
	v_max_i32_e32 v3, 0, v99
	v_fmac_f32_e32 v4, v2, v175
	v_fmac_f32_e32 v4, v3, v176
	v_add_f32_e32 v4, 0, v4
	v_ashrrev_i32_e32 v5, 31, v4
	v_bitop3_b32 v4, v5, v4, s81 bitop3:0x36
	v_and_or_b32 v6, v4, s82, v13
	v_cmp_ge_u32_e64 s[26:27], v6, v216
	v_cmp_le_i32_e64 s[28:29], v215, v152
	v_mov_b32_e32 v9, s52
	v_mov_b32_e32 v10, s53
	s_and_b64 s[26:27], s[26:27], s[28:29]
	v_cndmask_b32_e64 v9, v10, v9, s[4:5]
	v_mbcnt_lo_u32_b32 v7, s26, 0
	v_mbcnt_hi_u32_b32 v8, s27, 0
	s_bcnt1_i32_b32 s30, s26
	s_bcnt1_i32_b32 s31, s27
	v_cndmask_b32_e64 v7, v8, v7, s[4:5]
	v_add_lshl_u32 v12, v9, v7, 2
	v_add_u32_e32 v12, v12, v214
	s_mov_b64 exec, s[26:27]
	ds_write_b32 v12, v6
	s_mov_b64 exec, -1
	s_add_u32 s52, s52, s30
	s_add_u32 s53, s53, s31
	v_max_i32_e32 v0, 0, v100
	v_max_i32_e32 v1, 0, v101
	v_mul_f32_e32 v4, v177, v0
	v_max_i32_e32 v2, 0, v102
	v_fmac_f32_e32 v4, v1, v178
	v_max_i32_e32 v3, 0, v103
	v_fmac_f32_e32 v4, v2, v179
	v_fmac_f32_e32 v4, v3, v180
	v_add_f32_e32 v4, 0, v4
	v_ashrrev_i32_e32 v5, 31, v4
	v_bitop3_b32 v4, v5, v4, s81 bitop3:0x36
	v_and_or_b32 v6, v4, s82, v13
	v_cmp_ge_u32_e64 s[26:27], v6, v218
	v_cmp_le_i32_e64 s[28:29], v215, v154
	v_mov_b32_e32 v9, s54
	v_mov_b32_e32 v10, s55
	s_and_b64 s[26:27], s[26:27], s[28:29]
	v_cndmask_b32_e64 v9, v10, v9, s[4:5]
	v_mbcnt_lo_u32_b32 v7, s26, 0
	v_mbcnt_hi_u32_b32 v8, s27, 0
	s_bcnt1_i32_b32 s30, s26
	s_bcnt1_i32_b32 s31, s27
	v_cndmask_b32_e64 v7, v8, v7, s[4:5]
	v_add_lshl_u32 v12, v9, v7, 2
	v_add_u32_e32 v12, v12, v214
	s_mov_b64 exec, s[26:27]
	ds_write_b32 v12, v6 offset:4096
	s_mov_b64 exec, -1
	s_add_u32 s54, s54, s30
	s_add_u32 s55, s55, s31
	v_max_i32_e32 v0, 0, v104
	v_max_i32_e32 v1, 0, v105
	v_mul_f32_e32 v4, v181, v0
	v_max_i32_e32 v2, 0, v106
	v_fmac_f32_e32 v4, v1, v182
	v_max_i32_e32 v3, 0, v107
	v_fmac_f32_e32 v4, v2, v183
	v_fmac_f32_e32 v4, v3, v184
	v_add_f32_e32 v4, 0, v4
	v_ashrrev_i32_e32 v5, 31, v4
	v_bitop3_b32 v4, v5, v4, s81 bitop3:0x36
	v_and_or_b32 v6, v4, s82, v13
	v_cmp_ge_u32_e64 s[26:27], v6, v220
	v_cmp_le_i32_e64 s[28:29], v215, v156
	v_mov_b32_e32 v9, s56
	v_mov_b32_e32 v10, s57
	s_and_b64 s[26:27], s[26:27], s[28:29]
	v_cndmask_b32_e64 v9, v10, v9, s[4:5]
	v_mbcnt_lo_u32_b32 v7, s26, 0
	v_mbcnt_hi_u32_b32 v8, s27, 0
	s_bcnt1_i32_b32 s30, s26
	s_bcnt1_i32_b32 s31, s27
	v_cndmask_b32_e64 v7, v8, v7, s[4:5]
	v_add_lshl_u32 v12, v9, v7, 2
	v_add_u32_e32 v12, v12, v214
	s_mov_b64 exec, s[26:27]
	ds_write_b32 v12, v6 offset:8192
	s_mov_b64 exec, -1
	s_add_u32 s56, s56, s30
	s_add_u32 s57, s57, s31
	v_max_i32_e32 v0, 0, v108
	v_max_i32_e32 v1, 0, v109
	v_mul_f32_e32 v4, v185, v0
	v_max_i32_e32 v2, 0, v110
	v_fmac_f32_e32 v4, v1, v186
	v_max_i32_e32 v3, 0, v111
	v_fmac_f32_e32 v4, v2, v187
	v_fmac_f32_e32 v4, v3, v188
	v_add_f32_e32 v4, 0, v4
	v_ashrrev_i32_e32 v5, 31, v4
	v_bitop3_b32 v4, v5, v4, s81 bitop3:0x36
	v_and_or_b32 v6, v4, s82, v13
	v_cmp_ge_u32_e64 s[26:27], v6, v222
	v_cmp_le_i32_e64 s[28:29], v215, v158
	v_mov_b32_e32 v9, s58
	v_mov_b32_e32 v10, s59
	s_and_b64 s[26:27], s[26:27], s[28:29]
	v_cndmask_b32_e64 v9, v10, v9, s[4:5]
	v_mbcnt_lo_u32_b32 v7, s26, 0
	v_mbcnt_hi_u32_b32 v8, s27, 0
	s_bcnt1_i32_b32 s30, s26
	s_bcnt1_i32_b32 s31, s27
	v_cndmask_b32_e64 v7, v8, v7, s[4:5]
	v_add_lshl_u32 v12, v9, v7, 2
	v_add_u32_e32 v12, v12, v214
	s_mov_b64 exec, s[26:27]
	ds_write_b32 v12, v6 offset:12288
	s_mov_b64 exec, -1
	s_add_u32 s58, s58, s30
	s_add_u32 s59, s59, s31
	s_add_u32 s60, s60, 1
	s_cmp_gt_u32 s60, s61
	s_cbranch_scc1 .Lidx_done
.Lidx_tile1:
	s_add_u32 s62, s60, 3
	s_min_u32 s62, s62, s61
	s_lshl_b32 s62, s62, 12
	v_add_u32_e32 v14, s62, v11
	global_load_dwordx4 v[32:35], v14, s[64:65]
	global_load_dwordx4 v[36:39], v14, s[64:65] offset:1024
	global_load_dwordx4 v[40:43], v14, s[64:65] offset:2048
	global_load_dwordx4 v[44:47], v14, s[64:65] offset:3072
	s_max_u32 s62, s52, s53
	s_max_u32 s63, s54, s55
	s_max_u32 s62, s62, s63
	s_max_u32 s63, s56, s57
	s_max_u32 s62, s62, s63
	s_max_u32 s63, s58, s59
	s_max_u32 s62, s62, s63
	s_cmp_gt_u32 s62, s80
	s_cbranch_scc1 .Lidx_compact1
.Lidx_resume1:
	s_waitcnt vmcnt(8)
	v_mfma_f32_32x32x16_bf16 v[96:111], v[24:27], v[64:67], 0
	v_mfma_f32_32x32x16_bf16 v[96:111], v[16:19], v[68:71], v[96:111]
	v_mfma_f32_32x32x16_bf16 v[96:111], v[20:23], v[72:75], v[96:111]
	v_mfma_f32_32x32x16_bf16 v[96:111], v[28:31], v[76:79], v[96:111]
	s_lshl_b32 s62, s60, 5
	v_add_u32_e32 v215, s62, v157
	v_sub_u32_e32 v13, 0x3fff, v215
	v_max_i32_e32 v0, 0, v112
	v_max_i32_e32 v1, 0, v113
	v_mul_f32_e32 v4, v159, v0
	v_max_i32_e32 v2, 0, v114
	v_fmac_f32_e32 v4, v1, v174
	v_max_i32_e32 v3, 0, v115
	v_fmac_f32_e32 v4, v2, v175
	v_fmac_f32_e32 v4, v3, v176
	v_add_f32_e32 v4, 0, v4
	v_ashrrev_i32_e32 v5, 31, v4
	v_bitop3_b32 v4, v5, v4, s81 bitop3:0x36
	v_and_or_b32 v6, v4, s82, v13
	v_cmp_ge_u32_e64 s[26:27], v6, v216
	v_cmp_le_i32_e64 s[28:29], v215, v152
	v_mov_b32_e32 v9, s52
	v_mov_b32_e32 v10, s53
	s_and_b64 s[26:27], s[26:27], s[28:29]
	v_cndmask_b32_e64 v9, v10, v9, s[4:5]
	v_mbcnt_lo_u32_b32 v7, s26, 0
	v_mbcnt_hi_u32_b32 v8, s27, 0
	s_bcnt1_i32_b32 s30, s26
	s_bcnt1_i32_b32 s31, s27
	v_cndmask_b32_e64 v7, v8, v7, s[4:5]
	v_add_lshl_u32 v12, v9, v7, 2
	v_add_u32_e32 v12, v12, v214
	s_mov_b64 exec, s[26:27]
	ds_write_b32 v12, v6
	s_mov_b64 exec, -1
	s_add_u32 s52, s52, s30
	s_add_u32 s53, s53, s31
	v_max_i32_e32 v0, 0, v116
	v_max_i32_e32 v1, 0, v117
	v_mul_f32_e32 v4, v177, v0
	v_max_i32_e32 v2, 0, v118
	v_fmac_f32_e32 v4, v1, v178
	v_max_i32_e32 v3, 0, v119
	v_fmac_f32_e32 v4, v2, v179
	v_fmac_f32_e32 v4, v3, v180
	v_add_f32_e32 v4, 0, v4
	v_ashrrev_i32_e32 v5, 31, v4
	v_bitop3_b32 v4, v5, v4, s81 bitop3:0x36
	v_and_or_b32 v6, v4, s82, v13
	v_cmp_ge_u32_e64 s[26:27], v6, v218
	v_cmp_le_i32_e64 s[28:29], v215, v154
	v_mov_b32_e32 v9, s54
	v_mov_b32_e32 v10, s55
	s_and_b64 s[26:27], s[26:27], s[28:29]
	v_cndmask_b32_e64 v9, v10, v9, s[4:5]
	v_mbcnt_lo_u32_b32 v7, s26, 0
	v_mbcnt_hi_u32_b32 v8, s27, 0
	s_bcnt1_i32_b32 s30, s26
	s_bcnt1_i32_b32 s31, s27
	v_cndmask_b32_e64 v7, v8, v7, s[4:5]
	v_add_lshl_u32 v12, v9, v7, 2
	v_add_u32_e32 v12, v12, v214
	s_mov_b64 exec, s[26:27]
	ds_write_b32 v12, v6 offset:4096
	s_mov_b64 exec, -1
	s_add_u32 s54, s54, s30
	s_add_u32 s55, s55, s31
	v_max_i32_e32 v0, 0, v120
	v_max_i32_e32 v1, 0, v121
	v_mul_f32_e32 v4, v181, v0
	v_max_i32_e32 v2, 0, v122
	v_fmac_f32_e32 v4, v1, v182
	v_max_i32_e32 v3, 0, v123
	v_fmac_f32_e32 v4, v2, v183
	v_fmac_f32_e32 v4, v3, v184
	v_add_f32_e32 v4, 0, v4
	v_ashrrev_i32_e32 v5, 31, v4
	v_bitop3_b32 v4, v5, v4, s81 bitop3:0x36
	v_and_or_b32 v6, v4, s82, v13
	v_cmp_ge_u32_e64 s[26:27], v6, v220
	v_cmp_le_i32_e64 s[28:29], v215, v156
	v_mov_b32_e32 v9, s56
	v_mov_b32_e32 v10, s57
	s_and_b64 s[26:27], s[26:27], s[28:29]
	v_cndmask_b32_e64 v9, v10, v9, s[4:5]
	v_mbcnt_lo_u32_b32 v7, s26, 0
	v_mbcnt_hi_u32_b32 v8, s27, 0
	s_bcnt1_i32_b32 s30, s26
	s_bcnt1_i32_b32 s31, s27
	v_cndmask_b32_e64 v7, v8, v7, s[4:5]
	v_add_lshl_u32 v12, v9, v7, 2
	v_add_u32_e32 v12, v12, v214
	s_mov_b64 exec, s[26:27]
	ds_write_b32 v12, v6 offset:8192
	s_mov_b64 exec, -1
	s_add_u32 s56, s56, s30
	s_add_u32 s57, s57, s31
	v_max_i32_e32 v0, 0, v124
	v_max_i32_e32 v1, 0, v125
	v_mul_f32_e32 v4, v185, v0
	v_max_i32_e32 v2, 0, v126
	v_fmac_f32_e32 v4, v1, v186
	v_max_i32_e32 v3, 0, v127
	v_fmac_f32_e32 v4, v2, v187
	v_fmac_f32_e32 v4, v3, v188
	v_add_f32_e32 v4, 0, v4
	v_ashrrev_i32_e32 v5, 31, v4
	v_bitop3_b32 v4, v5, v4, s81 bitop3:0x36
	v_and_or_b32 v6, v4, s82, v13
	v_cmp_ge_u32_e64 s[26:27], v6, v222
	v_cmp_le_i32_e64 s[28:29], v215, v158
	v_mov_b32_e32 v9, s58
	v_mov_b32_e32 v10, s59
	s_and_b64 s[26:27], s[26:27], s[28:29]
	v_cndmask_b32_e64 v9, v10, v9, s[4:5]
	v_mbcnt_lo_u32_b32 v7, s26, 0
	v_mbcnt_hi_u32_b32 v8, s27, 0
	s_bcnt1_i32_b32 s30, s26
	s_bcnt1_i32_b32 s31, s27
	v_cndmask_b32_e64 v7, v8, v7, s[4:5]
	v_add_lshl_u32 v12, v9, v7, 2
	v_add_u32_e32 v12, v12, v214
	s_mov_b64 exec, s[26:27]
	ds_write_b32 v12, v6 offset:12288
	s_mov_b64 exec, -1
	s_add_u32 s58, s58, s30
	s_add_u32 s59, s59, s31
	s_add_u32 s60, s60, 1
	s_cmp_gt_u32 s60, s61
	s_cbranch_scc1 .Lidx_done
.Lidx_tile2:
	s_add_u32 s62, s60, 3
	s_min_u32 s62, s62, s61
	s_lshl_b32 s62, s62, 12
	v_add_u32_e32 v14, s62, v11
	global_load_dwordx4 v[48:51], v14, s[64:65]
	global_load_dwordx4 v[52:55], v14, s[64:65] offset:1024
	global_load_dwordx4 v[56:59], v14, s[64:65] offset:2048
	global_load_dwordx4 v[60:63], v14, s[64:65] offset:3072
	s_max_u32 s62, s52, s53
	s_max_u32 s63, s54, s55
	s_max_u32 s62, s62, s63
	s_max_u32 s63, s56, s57
	s_max_u32 s62, s62, s63
	s_max_u32 s63, s58, s59
	s_max_u32 s62, s62, s63
	s_cmp_gt_u32 s62, s80
	s_cbranch_scc1 .Lidx_compact2
.Lidx_resume2:
	s_waitcnt vmcnt(8)
	v_mfma_f32_32x32x16_bf16 v[112:127], v[24:27], v[80:83], 0
	v_mfma_f32_32x32x16_bf16 v[112:127], v[16:19], v[84:87], v[112:127]
	v_mfma_f32_32x32x16_bf16 v[112:127], v[20:23], v[88:91], v[112:127]
	v_mfma_f32_32x32x16_bf16 v[112:127], v[28:31], v[92:95], v[112:127]
	s_lshl_b32 s62, s60, 5
	v_add_u32_e32 v215, s62, v157
	v_sub_u32_e32 v13, 0x3fff, v215
	v_max_i32_e32 v0, 0, v96
	v_max_i32_e32 v1, 0, v97
	v_mul_f32_e32 v4, v159, v0
	v_max_i32_e32 v2, 0, v98
	v_fmac_f32_e32 v4, v1, v174
	v_max_i32_e32 v3, 0, v99
	v_fmac_f32_e32 v4, v2, v175
	v_fmac_f32_e32 v4, v3, v176
	v_add_f32_e32 v4, 0, v4
	v_ashrrev_i32_e32 v5, 31, v4
	v_bitop3_b32 v4, v5, v4, s81 bitop3:0x36
	v_and_or_b32 v6, v4, s82, v13
	v_cmp_ge_u32_e64 s[26:27], v6, v216
	v_cmp_le_i32_e64 s[28:29], v215, v152
	v_mov_b32_e32 v9, s52
	v_mov_b32_e32 v10, s53
	s_and_b64 s[26:27], s[26:27], s[28:29]
	v_cndmask_b32_e64 v9, v10, v9, s[4:5]
	v_mbcnt_lo_u32_b32 v7, s26, 0
	v_mbcnt_hi_u32_b32 v8, s27, 0
	s_bcnt1_i32_b32 s30, s26
	s_bcnt1_i32_b32 s31, s27
	v_cndmask_b32_e64 v7, v8, v7, s[4:5]
	v_add_lshl_u32 v12, v9, v7, 2
	v_add_u32_e32 v12, v12, v214
	s_mov_b64 exec, s[26:27]
	ds_write_b32 v12, v6
	s_mov_b64 exec, -1
	s_add_u32 s52, s52, s30
	s_add_u32 s53, s53, s31
	v_max_i32_e32 v0, 0, v100
	v_max_i32_e32 v1, 0, v101
	v_mul_f32_e32 v4, v177, v0
	v_max_i32_e32 v2, 0, v102
	v_fmac_f32_e32 v4, v1, v178
	v_max_i32_e32 v3, 0, v103
	v_fmac_f32_e32 v4, v2, v179
	v_fmac_f32_e32 v4, v3, v180
	v_add_f32_e32 v4, 0, v4
	v_ashrrev_i32_e32 v5, 31, v4
	v_bitop3_b32 v4, v5, v4, s81 bitop3:0x36
	v_and_or_b32 v6, v4, s82, v13
	v_cmp_ge_u32_e64 s[26:27], v6, v218
	v_cmp_le_i32_e64 s[28:29], v215, v154
	v_mov_b32_e32 v9, s54
	v_mov_b32_e32 v10, s55
	s_and_b64 s[26:27], s[26:27], s[28:29]
	v_cndmask_b32_e64 v9, v10, v9, s[4:5]
	v_mbcnt_lo_u32_b32 v7, s26, 0
	v_mbcnt_hi_u32_b32 v8, s27, 0
	s_bcnt1_i32_b32 s30, s26
	s_bcnt1_i32_b32 s31, s27
	v_cndmask_b32_e64 v7, v8, v7, s[4:5]
	v_add_lshl_u32 v12, v9, v7, 2
	v_add_u32_e32 v12, v12, v214
	s_mov_b64 exec, s[26:27]
	ds_write_b32 v12, v6 offset:4096
	s_mov_b64 exec, -1
	s_add_u32 s54, s54, s30
	s_add_u32 s55, s55, s31
	v_max_i32_e32 v0, 0, v104
	v_max_i32_e32 v1, 0, v105
	v_mul_f32_e32 v4, v181, v0
	v_max_i32_e32 v2, 0, v106
	v_fmac_f32_e32 v4, v1, v182
	v_max_i32_e32 v3, 0, v107
	v_fmac_f32_e32 v4, v2, v183
	v_fmac_f32_e32 v4, v3, v184
	v_add_f32_e32 v4, 0, v4
	v_ashrrev_i32_e32 v5, 31, v4
	v_bitop3_b32 v4, v5, v4, s81 bitop3:0x36
	v_and_or_b32 v6, v4, s82, v13
	v_cmp_ge_u32_e64 s[26:27], v6, v220
	v_cmp_le_i32_e64 s[28:29], v215, v156
	v_mov_b32_e32 v9, s56
	v_mov_b32_e32 v10, s57
	s_and_b64 s[26:27], s[26:27], s[28:29]
	v_cndmask_b32_e64 v9, v10, v9, s[4:5]
	v_mbcnt_lo_u32_b32 v7, s26, 0
	v_mbcnt_hi_u32_b32 v8, s27, 0
	s_bcnt1_i32_b32 s30, s26
	s_bcnt1_i32_b32 s31, s27
	v_cndmask_b32_e64 v7, v8, v7, s[4:5]
	v_add_lshl_u32 v12, v9, v7, 2
	v_add_u32_e32 v12, v12, v214
	s_mov_b64 exec, s[26:27]
	ds_write_b32 v12, v6 offset:8192
	s_mov_b64 exec, -1
	s_add_u32 s56, s56, s30
	s_add_u32 s57, s57, s31
	v_max_i32_e32 v0, 0, v108
	v_max_i32_e32 v1, 0, v109
	v_mul_f32_e32 v4, v185, v0
	v_max_i32_e32 v2, 0, v110
	v_fmac_f32_e32 v4, v1, v186
	v_max_i32_e32 v3, 0, v111
	v_fmac_f32_e32 v4, v2, v187
	v_fmac_f32_e32 v4, v3, v188
	v_add_f32_e32 v4, 0, v4
	v_ashrrev_i32_e32 v5, 31, v4
	v_bitop3_b32 v4, v5, v4, s81 bitop3:0x36
	v_and_or_b32 v6, v4, s82, v13
	v_cmp_ge_u32_e64 s[26:27], v6, v222
	v_cmp_le_i32_e64 s[28:29], v215, v158
	v_mov_b32_e32 v9, s58
	v_mov_b32_e32 v10, s59
	s_and_b64 s[26:27], s[26:27], s[28:29]
	v_cndmask_b32_e64 v9, v10, v9, s[4:5]
	v_mbcnt_lo_u32_b32 v7, s26, 0
	v_mbcnt_hi_u32_b32 v8, s27, 0
	s_bcnt1_i32_b32 s30, s26
	s_bcnt1_i32_b32 s31, s27
	v_cndmask_b32_e64 v7, v8, v7, s[4:5]
	v_add_lshl_u32 v12, v9, v7, 2
	v_add_u32_e32 v12, v12, v214
	s_mov_b64 exec, s[26:27]
	ds_write_b32 v12, v6 offset:12288
	s_mov_b64 exec, -1
	s_add_u32 s58, s58, s30
	s_add_u32 s59, s59, s31
	s_add_u32 s60, s60, 1
	s_cmp_gt_u32 s60, s61
	s_cbranch_scc1 .Lidx_done
.Lidx_tile3:
	s_add_u32 s62, s60, 3
	s_min_u32 s62, s62, s61
	s_lshl_b32 s62, s62, 12
	v_add_u32_e32 v14, s62, v11
	global_load_dwordx4 v[64:67], v14, s[64:65]
	global_load_dwordx4 v[68:71], v14, s[64:65] offset:1024
	global_load_dwordx4 v[72:75], v14, s[64:65] offset:2048
	global_load_dwordx4 v[76:79], v14, s[64:65] offset:3072
	s_max_u32 s62, s52, s53
	s_max_u32 s63, s54, s55
	s_max_u32 s62, s62, s63
	s_max_u32 s63, s56, s57
	s_max_u32 s62, s62, s63
	s_max_u32 s63, s58, s59
	s_max_u32 s62, s62, s63
	s_cmp_gt_u32 s62, s80
	s_cbranch_scc1 .Lidx_compact3
.Lidx_resume3:
	s_waitcnt vmcnt(8)
	v_mfma_f32_32x32x16_bf16 v[96:111], v[24:27], v[32:35], 0
	v_mfma_f32_32x32x16_bf16 v[96:111], v[16:19], v[36:39], v[96:111]
	v_mfma_f32_32x32x16_bf16 v[96:111], v[20:23], v[40:43], v[96:111]
	v_mfma_f32_32x32x16_bf16 v[96:111], v[28:31], v[44:47], v[96:111]
	s_lshl_b32 s62, s60, 5
	v_add_u32_e32 v215, s62, v157
	v_sub_u32_e32 v13, 0x3fff, v215
	v_max_i32_e32 v0, 0, v112
	v_max_i32_e32 v1, 0, v113
	v_mul_f32_e32 v4, v159, v0
	v_max_i32_e32 v2, 0, v114
	v_fmac_f32_e32 v4, v1, v174
	v_max_i32_e32 v3, 0, v115
	v_fmac_f32_e32 v4, v2, v175
	v_fmac_f32_e32 v4, v3, v176
	v_add_f32_e32 v4, 0, v4
	v_ashrrev_i32_e32 v5, 31, v4
	v_bitop3_b32 v4, v5, v4, s81 bitop3:0x36
	v_and_or_b32 v6, v4, s82, v13
	v_cmp_ge_u32_e64 s[26:27], v6, v216
	v_cmp_le_i32_e64 s[28:29], v215, v152
	v_mov_b32_e32 v9, s52
	v_mov_b32_e32 v10, s53
	s_and_b64 s[26:27], s[26:27], s[28:29]
	v_cndmask_b32_e64 v9, v10, v9, s[4:5]
	v_mbcnt_lo_u32_b32 v7, s26, 0
	v_mbcnt_hi_u32_b32 v8, s27, 0
	s_bcnt1_i32_b32 s30, s26
	s_bcnt1_i32_b32 s31, s27
	v_cndmask_b32_e64 v7, v8, v7, s[4:5]
	v_add_lshl_u32 v12, v9, v7, 2
	v_add_u32_e32 v12, v12, v214
	s_mov_b64 exec, s[26:27]
	ds_write_b32 v12, v6
	s_mov_b64 exec, -1
	s_add_u32 s52, s52, s30
	s_add_u32 s53, s53, s31
	v_max_i32_e32 v0, 0, v116
	v_max_i32_e32 v1, 0, v117
	v_mul_f32_e32 v4, v177, v0
	v_max_i32_e32 v2, 0, v118
	v_fmac_f32_e32 v4, v1, v178
	v_max_i32_e32 v3, 0, v119
	v_fmac_f32_e32 v4, v2, v179
	v_fmac_f32_e32 v4, v3, v180
	v_add_f32_e32 v4, 0, v4
	v_ashrrev_i32_e32 v5, 31, v4
	v_bitop3_b32 v4, v5, v4, s81 bitop3:0x36
	v_and_or_b32 v6, v4, s82, v13
	v_cmp_ge_u32_e64 s[26:27], v6, v218
	v_cmp_le_i32_e64 s[28:29], v215, v154
	v_mov_b32_e32 v9, s54
	v_mov_b32_e32 v10, s55
	s_and_b64 s[26:27], s[26:27], s[28:29]
	v_cndmask_b32_e64 v9, v10, v9, s[4:5]
	v_mbcnt_lo_u32_b32 v7, s26, 0
	v_mbcnt_hi_u32_b32 v8, s27, 0
	s_bcnt1_i32_b32 s30, s26
	s_bcnt1_i32_b32 s31, s27
	v_cndmask_b32_e64 v7, v8, v7, s[4:5]
	v_add_lshl_u32 v12, v9, v7, 2
	v_add_u32_e32 v12, v12, v214
	s_mov_b64 exec, s[26:27]
	ds_write_b32 v12, v6 offset:4096
	s_mov_b64 exec, -1
	s_add_u32 s54, s54, s30
	s_add_u32 s55, s55, s31
	v_max_i32_e32 v0, 0, v120
	v_max_i32_e32 v1, 0, v121
	v_mul_f32_e32 v4, v181, v0
	v_max_i32_e32 v2, 0, v122
	v_fmac_f32_e32 v4, v1, v182
	v_max_i32_e32 v3, 0, v123
	v_fmac_f32_e32 v4, v2, v183
	v_fmac_f32_e32 v4, v3, v184
	v_add_f32_e32 v4, 0, v4
	v_ashrrev_i32_e32 v5, 31, v4
	v_bitop3_b32 v4, v5, v4, s81 bitop3:0x36
	v_and_or_b32 v6, v4, s82, v13
	v_cmp_ge_u32_e64 s[26:27], v6, v220
	v_cmp_le_i32_e64 s[28:29], v215, v156
	v_mov_b32_e32 v9, s56
	v_mov_b32_e32 v10, s57
	s_and_b64 s[26:27], s[26:27], s[28:29]
	v_cndmask_b32_e64 v9, v10, v9, s[4:5]
	v_mbcnt_lo_u32_b32 v7, s26, 0
	v_mbcnt_hi_u32_b32 v8, s27, 0
	s_bcnt1_i32_b32 s30, s26
	s_bcnt1_i32_b32 s31, s27
	v_cndmask_b32_e64 v7, v8, v7, s[4:5]
	v_add_lshl_u32 v12, v9, v7, 2
	v_add_u32_e32 v12, v12, v214
	s_mov_b64 exec, s[26:27]
	ds_write_b32 v12, v6 offset:8192
	s_mov_b64 exec, -1
	s_add_u32 s56, s56, s30
	s_add_u32 s57, s57, s31
	v_max_i32_e32 v0, 0, v124
	v_max_i32_e32 v1, 0, v125
	v_mul_f32_e32 v4, v185, v0
	v_max_i32_e32 v2, 0, v126
	v_fmac_f32_e32 v4, v1, v186
	v_max_i32_e32 v3, 0, v127
	v_fmac_f32_e32 v4, v2, v187
	v_fmac_f32_e32 v4, v3, v188
	v_add_f32_e32 v4, 0, v4
	v_ashrrev_i32_e32 v5, 31, v4
	v_bitop3_b32 v4, v5, v4, s81 bitop3:0x36
	v_and_or_b32 v6, v4, s82, v13
	v_cmp_ge_u32_e64 s[26:27], v6, v222
	v_cmp_le_i32_e64 s[28:29], v215, v158
	v_mov_b32_e32 v9, s58
	v_mov_b32_e32 v10, s59
	s_and_b64 s[26:27], s[26:27], s[28:29]
	v_cndmask_b32_e64 v9, v10, v9, s[4:5]
	v_mbcnt_lo_u32_b32 v7, s26, 0
	v_mbcnt_hi_u32_b32 v8, s27, 0
	s_bcnt1_i32_b32 s30, s26
	s_bcnt1_i32_b32 s31, s27
	v_cndmask_b32_e64 v7, v8, v7, s[4:5]
	v_add_lshl_u32 v12, v9, v7, 2
	v_add_u32_e32 v12, v12, v214
	s_mov_b64 exec, s[26:27]
	ds_write_b32 v12, v6 offset:12288
	s_mov_b64 exec, -1
	s_add_u32 s58, s58, s30
	s_add_u32 s59, s59, s31
	s_add_u32 s60, s60, 1
	s_cmp_gt_u32 s60, s61
	s_cbranch_scc1 .Lidx_done
	s_branch .Lidx_loop
.Lidx_compact0:
	s_mov_b32 s67, 0
	s_branch .Lidx_compact
.Lidx_compact1:
	s_mov_b32 s67, 1
	s_branch .Lidx_compact
.Lidx_compact2:
	s_mov_b32 s67, 2
	s_branch .Lidx_compact
.Lidx_compact3:
	s_mov_b32 s67, 3
	s_branch .Lidx_compact
.Lidx_compact:
	v_writelane_b32 v173, s52, 0
	v_writelane_b32 v173, s53, 1
	v_writelane_b32 v173, s54, 2
	v_writelane_b32 v173, s55, 3
	v_writelane_b32 v173, s56, 4
	v_writelane_b32 v173, s57, 5
	v_writelane_b32 v173, s58, 6
	v_writelane_b32 v173, s59, 7
	s_nop 1
	v_cmp_lt_i32_e32 vcc, s80, v173
	s_and_b64 s[0:1], s[8:9], vcc
	s_branch .LBB0_549
.Lidx_done:
	v_writelane_b32 v173, s52, 0
	v_writelane_b32 v173, s53, 1
	v_writelane_b32 v173, s54, 2
	v_writelane_b32 v173, s55, 3
	v_writelane_b32 v173, s56, 4
	v_writelane_b32 v173, s57, 5
	v_writelane_b32 v173, s58, 6
	v_writelane_b32 v173, s59, 7
	s_branch .LBB0_1451

.LBB0_616:
	v_readlane_b32 s0, v144, 0
	v_readlane_b32 s1, v144, 1
	s_nop 0
	v_mov_b32_e32 v1, s0
	v_mov_b32_e32 v0, s1
	v_cndmask_b32_e64 v216, v0, v1, s[4:5]
	v_cmp_lt_i32_e32 vcc, -1, v216
	v_readlane_b32 s0, v144, 2
	v_readlane_b32 s1, v144, 3
	v_cndmask_b32_e64 v0, v207, -1, vcc
	v_bitop3_b32 v0, v0, v216, s82 bitop3:0x78
	v_cmp_ne_u32_e32 vcc, 0, v216
	v_mov_b32_e32 v1, s0
	v_readlane_b32 s0, v144, 4
	v_cndmask_b32_e32 v217, v208, v0, vcc
	v_mov_b32_e32 v0, s1
	v_cndmask_b32_e64 v218, v0, v1, s[4:5]
	v_cmp_lt_i32_e32 vcc, -1, v218
	v_readlane_b32 s1, v144, 5
	v_mov_b32_e32 v1, s0
	v_cndmask_b32_e64 v0, v207, -1, vcc
	v_bitop3_b32 v0, v0, v218, s82 bitop3:0x78
	v_cmp_ne_u32_e32 vcc, 0, v218
	v_readlane_b32 s0, v144, 6
	s_nop 0
	v_cndmask_b32_e32 v219, v208, v0, vcc
	v_mov_b32_e32 v0, s1
	v_cndmask_b32_e64 v220, v0, v1, s[4:5]
	v_cmp_lt_i32_e32 vcc, -1, v220
	v_readlane_b32 s1, v144, 7
	v_mov_b32_e32 v1, s0
	v_cndmask_b32_e64 v0, v207, -1, vcc
	v_bitop3_b32 v0, v0, v220, s82 bitop3:0x78
	v_cmp_ne_u32_e32 vcc, 0, v220
	s_nop 1
	v_cndmask_b32_e32 v221, v208, v0, vcc
	v_mov_b32_e32 v0, s1
	v_cndmask_b32_e64 v222, v0, v1, s[4:5]
	v_cmp_lt_i32_e32 vcc, -1, v222
	s_nop 1
	v_cndmask_b32_e64 v0, v207, -1, vcc
	v_bitop3_b32 v0, v0, v222, s82 bitop3:0x78
	v_cmp_ne_u32_e32 vcc, 0, v222
	s_nop 1
	v_cndmask_b32_e32 v223, v208, v0, vcc
	s_nop 1
	v_readlane_b32 s52, v173, 0
	v_readlane_b32 s53, v173, 1
	v_readlane_b32 s54, v173, 2
	v_readlane_b32 s55, v173, 3
	v_readlane_b32 s56, v173, 4
	v_readlane_b32 s57, v173, 5
	v_readlane_b32 s58, v173, 6
	v_readlane_b32 s59, v173, 7
	s_cmp_eq_u32 s67, 0
	s_cbranch_scc1 .Lidx_resume0
	s_cmp_eq_u32 s67, 1
	s_cbranch_scc1 .Lidx_resume1
	s_cmp_eq_u32 s67, 2
	s_cbranch_scc1 .Lidx_resume2
	s_branch .Lidx_resume3
